# combined: up-epilogue LDS-DMA operand prefetch + leftover lgkmcnt(0) wait removal in all GEMM epilogues
# speedup vs baseline: 1.0071x; 1.0020x over previous
; __device__ __forceinline__ void load_row_scales(const float* ssp, int row0, int fq, float (&rs)[2][4]) {
;     f32x4 part[2][4];
;     const float* sp = ssp + (size_t)row0 * 16 + 4 * fq;
; #pragma unroll
;     for (int ai = 0; ai < 2; ++ai)
; #pragma unroll
;         for (int m = 0; m < 4; ++m) part[ai][m] = *(const f32x4*)(sp + (size_t)(ai * HALF + m * 16) * 16);
; #pragma unroll
;     for (int ai = 0; ai < 2; ++ai)
; #pragma unroll
;         for (int m = 0; m < 4; ++m) { float t = (part[ai][m][0] + part[ai][m][1]) + (part[ai][m][2] + part[ai][m][3]);
;             t += __shfl_xor(t, 16); t += __shfl_xor(t, 32);
;             rs[ai][m] = 1.0f / sqrtf(t * (1.0f / 1024.0f) + 1e-6f); }
;     __device__ __forceinline__ void operator()(f32x4 (&acc)[2][2][4][2], const Unit& u, int wr, int wc, int fr, int fq) const {
;     ...
;         for (int n = 0; n < 2; ++n) {
;             const int gc0 = u.pn * 128 + wc * 32 + 8 * fq + 4 * n;
;             const float* cwp = cw + gc0; asm volatile("" : "+v"(cwp));
;             const f32x4 wg0 = *(const f32x4*)(cwp), wg1 = *(const f32x4*)(cwp + FF2c), wg2 = *(const f32x4*)(cwp + 2 * FF2c);
;             const f32x4 wv0 = *(const f32x4*)(cwp + FFc), wv1 = *(const f32x4*)(cwp + FF2c + FFc), wv2 = *(const f32x4*)(cwp + 2 * FF2c + FFc);
;             const f32x4 bg = *(const f32x4*)(cb + gc0), bv = *(const f32x4*)(cb + FFc + gc0);
.LBB0_1350:
	s_lshl_b32 s13, s13, 8
	s_add_i32 s13, s13, s24
	v_or_b32_e32 v176, s13, v161
	v_ashrrev_i32_e32 v177, 31, v176
	v_lshlrev_b64 v[130:131], 6, v[176:177]
	v_lshl_add_u64 v[146:147], v[162:163], 0, v[130:131]
	global_load_dwordx4 v[130:133], v[146:147], off
	global_load_dwordx4 v[134:137], v[146:147], off offset:1024
	global_load_dwordx4 v[138:141], v[146:147], off offset:2048
	global_load_dwordx4 v[142:145], v[146:147], off offset:3072
	v_add_co_u32_e32 v168, vcc, 0x2000, v146
	v_mov_b32_e32 v177, v1
	s_nop 0
	v_addc_co_u32_e32 v169, vcc, 0, v147, vcc
	global_load_dwordx4 v[146:149], v[168:169], off
	global_load_dwordx4 v[150:153], v[168:169], off offset:1024
	global_load_dwordx4 v[170:173], v[168:169], off offset:2048
	global_load_dwordx4 v[178:181], v[168:169], off offset:3072
	v_and_b32_e32 v169, 64, v229
	v_xor_b32_e32 v168, 16, v229
	v_add_u32_e32 v169, 64, v169
	v_cmp_lt_i32_e32 vcc, v168, v169
	v_mov_b32_dpp v177, v177 row_ror:1 row_mask:0xf bank_mask:0xf
	v_mov_b32_e32 v189, v177
	v_cndmask_b32_e32 v168, v229, v168, vcc
	v_lshlrev_b32_e32 v174, 2, v168
	v_xor_b32_e32 v168, 32, v229
	v_cmp_lt_i32_e32 vcc, v168, v169
	s_waitcnt vmcnt(0)
	s_mov_b32 s100, 1
	v_mov_b32_e32 v169, v132
	v_cndmask_b32_e32 v168, v229, v168, vcc
	v_lshlrev_b32_e32 v175, 2, v168
	v_mov_b32_e32 v168, v131
	v_mov_b32_e32 v131, v133
	v_pk_add_f32 v[130:131], v[168:169], v[130:131]
	s_nop 0
	v_add_f32_e32 v130, v130, v131
	v_mov_b32_e32 v131, v130
	s_nop 1
	v_permlane16_swap_b32_e32 v131, v130
	s_waitcnt lgkmcnt(0)
	v_add_f32_e32 v130, v130, v131
	v_mov_b32_e32 v131, v130
	s_nop 1
	v_permlane32_swap_b32_e32 v131, v130
	v_add_f32_e32 v130, v130, v131
	v_fmamk_f32 v130, v130, 0x3a800000, v230
	s_ashr_i32 s0, s13, 5
	v_rsq_f32_e32 v168, v130
	s_nop 0
	v_mov_b32_e32 v130, v135
	v_mov_b32_e32 v131, v136
	v_mov_b32_e32 v135, v137
	v_pk_add_f32 v[130:131], v[130:131], v[134:135]
	s_nop 0
	v_add_f32_e32 v130, v130, v131
	v_mov_b32_e32 v131, v130
	s_nop 1
	v_permlane16_swap_b32_e32 v131, v130
	v_add_f32_e32 v205, v130, v131
	v_mov_b32_e32 v130, v139
	v_mov_b32_e32 v131, v140
	v_mov_b32_e32 v139, v141
	v_pk_add_f32 v[130:131], v[130:131], v[138:139]
	ds_bpermute_b32 v206, v175, v205
	v_add_f32_e32 v130, v130, v131
	v_mov_b32_e32 v131, v130
	s_nop 1
	v_permlane16_swap_b32_e32 v131, v130
	v_add_f32_e32 v203, v130, v131
	v_mov_b32_e32 v130, v143
	v_mov_b32_e32 v131, v144
	v_mov_b32_e32 v143, v145
	v_pk_add_f32 v[130:131], v[130:131], v[142:143]
	ds_bpermute_b32 v204, v175, v203
	v_add_f32_e32 v130, v130, v131
	v_mov_b32_e32 v131, v130
	s_nop 1
	v_permlane16_swap_b32_e32 v131, v130
	v_add_f32_e32 v182, v130, v131
	v_mov_b32_e32 v130, v147
	v_mov_b32_e32 v131, v148
	v_mov_b32_e32 v147, v149
	v_pk_add_f32 v[130:131], v[130:131], v[146:147]
	ds_bpermute_b32 v202, v175, v182
	v_add_f32_e32 v130, v130, v131
	v_mov_b32_e32 v131, v130
	s_nop 1
	v_permlane16_swap_b32_e32 v131, v130
	v_add_f32_e32 v244, v130, v131
	v_mov_b32_e32 v130, v151
	v_mov_b32_e32 v131, v152
	v_mov_b32_e32 v151, v153
	v_pk_add_f32 v[130:131], v[130:131], v[150:151]
	ds_bpermute_b32 v245, v175, v244
	v_add_f32_e32 v130, v130, v131
	v_mov_b32_e32 v131, v130
	s_nop 1
	v_permlane16_swap_b32_e32 v131, v130
	v_add_f32_e32 v242, v130, v131
	v_mov_b32_e32 v130, v171
	v_mov_b32_e32 v131, v172
	v_mov_b32_e32 v171, v173
	v_pk_add_f32 v[130:131], v[130:131], v[170:171]
	v_lshl_or_b32 v170, s12, 7, v238
	v_add_f32_e32 v130, v130, v131
	v_mov_b32_e32 v131, v130
	s_nop 1
	v_permlane16_swap_b32_e32 v131, v130
	v_ashrrev_i32_e32 v171, 31, v170
	v_lshlrev_b64 v[150:151], 2, v[170:171]
	v_lshl_add_u64 v[172:173], s[70:71], 0, v[150:151]
	ds_bpermute_b32 v243, v175, v242
	v_add_f32_e32 v240, v130, v131
	v_mov_b32_e32 v130, v179
	v_mov_b32_e32 v131, v180
	v_mov_b32_e32 v179, v181
	v_pk_add_f32 v[130:131], v[130:131], v[178:179]
	ds_bpermute_b32 v241, v175, v240
	v_add_f32_e32 v130, v130, v131
	v_mov_b32_e32 v131, v130
	s_nop 1
	v_permlane16_swap_b32_e32 v131, v130
	v_lshlrev_b64 v[178:179], 1, v[170:171]
	v_add_f32_e32 v169, v130, v131
	v_pk_mul_f32 v[196:197], v[98:99], v[168:169] op_sel_hi:[1,0]
	v_or_b32_e32 v98, s0, v160
	v_mad_i64_i32 v[200:201], s[0:1], v98, s37, 0
	v_pk_mul_f32 v[198:199], v[102:103], v[168:169] op_sel_hi:[1,0]
	v_mov_b64_e32 v[102:103], v[172:173]
	s_movk_i32 s0, 0x5000
	ds_bpermute_b32 v183, v175, v169
	v_add_co_u32_e32 v98, vcc, s0, v102
	s_mov_b32 s0, 0xb000
	s_nop 0
	v_addc_co_u32_e32 v99, vcc, 0, v103, vcc
	global_load_dwordx4 v[142:145], v[98:99], off offset:2048
	v_add_co_u32_e32 v98, vcc, s0, v102
	s_movk_i32 s0, 0x2000
	s_nop 0
	v_addc_co_u32_e32 v99, vcc, 0, v103, vcc
	v_pk_mul_f32 v[194:195], v[104:105], v[168:169] op_sel_hi:[1,0]
	v_add_co_u32_e32 v104, vcc, s0, v102
	v_lshl_add_u64 v[174:175], s[72:73], 0, v[150:151]
	global_load_dwordx4 v[138:141], v[102:103], off
	v_addc_co_u32_e32 v105, vcc, 0, v103, vcc
	s_mov_b32 s0, 0x8000
	global_load_dwordx4 v[146:149], v[174:175], off
	global_load_dwordx4 v[130:133], v[104:105], off offset:3072
	v_add_co_u32_e32 v104, vcc, s0, v102
	v_lshl_add_u64 v[150:151], s[76:77], 0, v[150:151]
	v_pk_mul_f32 v[192:193], v[100:101], v[168:169] op_sel_hi:[1,0]
	global_load_dwordx4 v[98:101], v[98:99], off
	v_addc_co_u32_e32 v105, vcc, 0, v103, vcc
	global_load_dwordx4 v[150:153], v[150:151], off
	s_mov_b32 s0, 0xd000
	global_load_dwordx4 v[134:137], v[104:105], off offset:1024
	v_add_co_u32_e32 v102, vcc, s0, v102
	v_readlane_b32 s0, v253, 44
	s_nop 0
	v_addc_co_u32_e32 v103, vcc, 0, v103, vcc
	global_load_dwordx4 v[102:105], v[102:103], off offset:3072
	v_readlane_b32 s1, v253, 45
	v_mov_b32_dpp v189, v196 row_shr:1 row_mask:0xf bank_mask:0xf
	s_nop 0
	v_lshl_add_u64 v[180:181], v[200:201], 1, s[0:1]
	v_lshl_add_u64 v[184:185], v[180:181], 0, v[178:179]
	v_mov_b32_e32 v181, v1
	v_mov_b32_e32 v180, v177
	s_nop 0
	v_mov_b32_dpp v181, v181 row_ror:2 row_mask:0xf bank_mask:0xf
	v_mov_b32_e32 v188, v181
	v_mov_b32_dpp v180, v198 row_shr:1 row_mask:0xf bank_mask:0xf
	v_mov_b32_e32 v190, v181
	v_mov_b32_dpp v188, v198 row_shr:2 row_mask:0xf bank_mask:0xf
	v_mov_b32_e32 v191, v181
	v_mov_b32_dpp v190, v196 row_shr:2 row_mask:0xf bank_mask:0xf
	v_mov_b32_e32 v207, v181
	v_mov_b32_dpp v191, v197 row_shr:2 row_mask:0xf bank_mask:0xf
	s_waitcnt vmcnt(0) lgkmcnt(0)
;     __device__ __forceinline__ void operator()(f32x4 (&acc)[2][2][4][2], const Unit& u, int wr, int wc, int fr, int fq) const {
;     ...
;         for (int n = 0; n < 2; ++n) {
;             const int gc0 = u.pn * 128 + wc * 32 + 8 * fq + 4 * n;
;             const float* cwp = cw + gc0; asm volatile("" : "+v"(cwp));
;             const f32x4 wg0 = *(const f32x4*)(cwp), wg1 = *(const f32x4*)(cwp + FF2c), wg2 = *(const f32x4*)(cwp + 2 * FF2c);
;             const f32x4 wv0 = *(const f32x4*)(cwp + FFc), wv1 = *(const f32x4*)(cwp + FF2c + FFc), wv2 = *(const f32x4*)(cwp + 2 * FF2c + FFc);
;             const f32x4 bg = *(const f32x4*)(cb + gc0), bv = *(const f32x4*)(cb + FFc + gc0);
;     ...
; #pragma unroll
;             for (int ai = 0; ai < 2; ++ai) {
; #pragma unroll
;                 for (int m = 0; m < 4; ++m) {
;                     float og[4];
; #pragma unroll
;                     for (int j = 0; j < 4; ++j) {
;                         const float vg = acc[ai][0][m][n][j], vv = acc[ai][1][m][n][j];
;                         const float pg = (m > 0) ? acc[ai][0][m - 1][n][j] : 0.f, pv = (m > 0) ? acc[ai][1][m - 1][n][j] : 0.f;
;                         const float g1 = dppf(dppf(0.f, pg, 2), vg, 0), g2 = dppf(dppf(0.f, pg, 3), vg, 1);
;                         const float v1 = dppf(dppf(0.f, pv, 2), vv, 0), v2 = dppf(dppf(0.f, pv, 3), vv, 1);
;                         const float cgate = bg[j] + wg0[j] * g2 + wg1[j] * g1 + wg2[j] * vg;
;                         const float cval = bv[j] + wv0[j] * v2 + wv1[j] * v1 + wv2[j] * vv;
;                         og[j] = cgate * __builtin_amdgcn_rcpf(1.0f + __builtin_amdgcn_exp2f(-1.4426950408889634f * cgate)) * cval; }
;                     const unsigned long long w = (unsigned long long)cvt_pk_bf16(og[0], og[1]) | ((unsigned long long)cvt_pk_bf16(og[2], og[3]) << 32);
;                     if (m == 0) {
;                         if (fr >= 2) *(unsigned long long*)gp = w;
;                         else { *(unsigned long long*)sb = (unsigned long long)cvt_pk_bf16(acc[ai][0][0][n][0], acc[ai][0][0][n][1]) | ((unsigned long long)cvt_pk_bf16(acc[ai][0][0][n][2], acc[ai][0][0][n][3]) << 32);
;                                *(unsigned long long*)(sb + FFc) = (unsigned long long)cvt_pk_bf16(acc[ai][1][0][n][0], acc[ai][1][0][n][1]) | ((unsigned long long)cvt_pk_bf16(acc[ai][1][0][n][2], acc[ai][1][0][n][3]) << 32); }
	v_mbcnt_lo_u32_b32 v231, -1, 0
	v_mbcnt_hi_u32_b32 v231, -1, v231
	v_lshrrev_b32_e32 v231, 4, v231
	v_lshl_add_u32 v231, v231, 8, s96
	v_add_u32_e32 v231, 0x20000, v231
	s_mov_b32 exec_lo, 0x10001
	s_mov_b32 exec_hi, 0x10001
	s_nop 1
	v_lshl_add_u64 v[220:221], v[172:173], 0, 16
	v_mov_b32_e32 v223, 0
	s_add_i32 m0, s96, 0x20000
	s_nop 0
	global_load_lds_dwordx4 v[220:221], off
	v_mov_b32_e32 v222, 0x5800
	s_add_i32 m0, s96, 0x20010
	v_lshl_add_u64 v[226:227], v[220:221], 0, v[222:223]
	global_load_lds_dwordx4 v[226:227], off
	v_mov_b32_e32 v222, 0xb000
	s_add_i32 m0, s96, 0x20020
	v_lshl_add_u64 v[224:225], v[220:221], 0, v[222:223]
	global_load_lds_dwordx4 v[224:225], off
	v_mov_b32_e32 v222, 0x2c00
	s_add_i32 m0, s96, 0x20030
	v_lshl_add_u64 v[226:227], v[220:221], 0, v[222:223]
	global_load_lds_dwordx4 v[226:227], off
	v_mov_b32_e32 v222, 0x8400
	s_add_i32 m0, s96, 0x20040
	v_lshl_add_u64 v[224:225], v[220:221], 0, v[222:223]
	global_load_lds_dwordx4 v[224:225], off
	v_mov_b32_e32 v222, 0xdc00
	s_add_i32 m0, s96, 0x20050
	v_lshl_add_u64 v[226:227], v[220:221], 0, v[222:223]
	global_load_lds_dwordx4 v[226:227], off
	s_add_i32 m0, s96, 0x20060
	v_lshl_add_u64 v[224:225], v[174:175], 0, 16
	global_load_lds_dwordx4 v[224:225], off
	v_or_b32_e32 v226, 4, v170
	s_add_i32 m0, s96, 0x20070
	v_ashrrev_i32_e32 v227, 31, v226
	v_lshl_add_u64 v[226:227], v[226:227], 2, s[76:77]
	global_load_lds_dwordx4 v[226:227], off
	s_mov_b64 exec, -1
	s_nop 1
	v_fma_f32 v188, v138, v188, v146
	v_fmac_f32_e32 v188, v142, v180
	v_mov_b32_dpp v207, v192 row_shr:2 row_mask:0xf bank_mask:0xf
	v_fmac_f32_e32 v188, v198, v98
	v_fma_f32 v180, v130, v190, v150
	v_mov_b32_e32 v190, v177
	v_fmac_f32_e32 v180, v134, v189
	v_mul_f32_e32 v189, 0xbfb8aa3b, v188
	v_exp_f32_e32 v189, v189
	v_mov_b32_dpp v190, v197 row_shr:1 row_mask:0xf bank_mask:0xf
	v_add_f32_e32 v189, 1.0, v189
	v_rcp_f32_e32 v189, v189
	v_fmac_f32_e32 v180, v196, v102
	v_mul_f32_e32 v188, v188, v189
	v_mov_b32_e32 v189, v181
	v_mul_f32_e32 v180, v180, v188
	v_mov_b32_e32 v188, v177
	v_mov_b32_dpp v189, v199 row_shr:2 row_mask:0xf bank_mask:0xf
	v_fma_f32 v189, v139, v189, v147
	v_mov_b32_dpp v188, v199 row_shr:1 row_mask:0xf bank_mask:0xf
	v_fmac_f32_e32 v189, v143, v188
	v_fmac_f32_e32 v189, v199, v99
	v_fma_f32 v188, v131, v191, v151
	v_fmac_f32_e32 v188, v135, v190
	v_mul_f32_e32 v190, 0xbfb8aa3b, v189
	v_exp_f32_e32 v190, v190
	v_fmac_f32_e32 v188, v197, v103
	v_mov_b32_e32 v191, v177
	v_add_f32_e32 v190, 1.0, v190
	v_rcp_f32_e32 v190, v190
	v_mov_b32_dpp v191, v192 row_shr:1 row_mask:0xf bank_mask:0xf
	v_mul_f32_e32 v189, v189, v190
	v_mov_b32_e32 v190, v181
	v_mul_f32_e32 v188, v188, v189
	v_mov_b32_e32 v189, v177
	v_mov_b32_dpp v190, v194 row_shr:2 row_mask:0xf bank_mask:0xf
	v_fma_f32 v190, v140, v190, v148
	v_mov_b32_dpp v189, v194 row_shr:1 row_mask:0xf bank_mask:0xf
	v_fmac_f32_e32 v190, v144, v189
	v_fmac_f32_e32 v190, v194, v100
	v_fma_f32 v189, v132, v207, v152
	v_fmac_f32_e32 v189, v136, v191
	v_mul_f32_e32 v191, 0xbfb8aa3b, v190
	v_exp_f32_e32 v191, v191
	v_fmac_f32_e32 v189, v192, v104
	v_cvt_pk_bf16_f32 v180, v180, v188
	v_add_f32_e32 v191, 1.0, v191
	v_rcp_f32_e32 v191, v191
	s_nop 0
	v_mul_f32_e32 v190, v190, v191
	v_mov_b32_e32 v191, v181
	v_mul_f32_e32 v189, v189, v190
	v_mov_b32_e32 v190, v177
	v_mov_b32_dpp v191, v195 row_shr:2 row_mask:0xf bank_mask:0xf
	v_fma_f32 v191, v141, v191, v149
	v_mov_b32_dpp v190, v195 row_shr:1 row_mask:0xf bank_mask:0xf
	v_mov_b32_dpp v181, v193 row_shr:2 row_mask:0xf bank_mask:0xf
	v_fmac_f32_e32 v191, v145, v190
	v_mov_b32_dpp v177, v193 row_shr:1 row_mask:0xf bank_mask:0xf
	v_fmac_f32_e32 v191, v195, v101
	v_fma_f32 v181, v133, v181, v153
	v_fmac_f32_e32 v181, v137, v177
	v_mul_f32_e32 v177, 0xbfb8aa3b, v191
	v_exp_f32_e32 v177, v177
	v_fmac_f32_e32 v181, v193, v105
	v_add_f32_e32 v177, 1.0, v177
	v_rcp_f32_e32 v177, v177
	s_nop 0
	v_mul_f32_e32 v177, v191, v177
	v_mul_f32_e32 v177, v181, v177
	v_cvt_pk_bf16_f32 v181, v189, v177
	s_and_saveexec_b64 s[0:1], s[6:7]
	s_xor_b64 s[0:1], exec, s[0:1]
	s_mov_b64 s[50:51], 0x16000
	s_mov_b64 s[52:53], 0x58000
	s_mov_b64 s[54:55], 0xb000
	s_cbranch_execz .LBB0_1352
	v_cvt_pk_bf16_f32 v180, v198, v199
	v_cvt_pk_bf16_f32 v181, v194, v195
	v_add_co_u32_e32 v188, vcc, 0x1000, v184
	global_store_dwordx2 v[184:185], v[180:181], off
	v_cvt_pk_bf16_f32 v180, v196, v197
	v_cvt_pk_bf16_f32 v181, v192, v193
	s_nop 0
	v_addc_co_u32_e32 v189, vcc, 0, v185, vcc
	global_store_dwordx2 v[188:189], v[180:181], off offset:1536
